# prep phase input loads marked nt (f32 inputs, weights and caches are each read once)
# baseline (speedup 1.0000x reference)
; __device__ __forceinline__ void phase_prep(KP kp, unsigned char* shm) {
;     ...
;       const TTile t = prep_tile(kp, ws, j0 + q);
; #pragma unroll
;       for (int e = 0; e < 8; ++e) {
;         const int idx = tid + e * 512, r = idx >> 6, c = idx & 63;
;         const int oc = t.winmap ? win_orig_col(t.n0 + c) : (t.n0 + c);
;         v[q][e] = oc >= 0 ? t.src[(size_t)(t.k0 + r) * t.ldsrc + oc] : 0.f;
;       }
.LBB0_505:
	v_add_u32_e32 v7, s24, v21
	v_ashrrev_i32_e32 v45, 31, v7
	v_mul_lo_u32 v45, s30, v45
	v_mul_lo_u32 v48, s31, v7
	v_mad_u64_u32 v[46:47], s[2:3], s30, v7, 0
	v_add3_u32 v47, v47, v45, v48
	v_mov_b32_e32 v7, v3
	v_lshl_add_u64 v[46:47], v[46:47], 2, s[28:29]
	v_lshl_add_u64 v[6:7], v[6:7], 2, v[46:47]
	global_load_dword v45, v[6:7], off nt
	s_or_b64 exec, exec, s[0:1]
	s_and_b64 vcc, exec, s[14:15]
	v_mov_b32_e32 v6, v4
	s_cbranch_vccz .LBB0_85

; __device__ __forceinline__ void phase_prep(KP kp, unsigned char* shm) {
;     ...
;       const TTile t = prep_tile(kp, ws, j0 + q);
; #pragma unroll
;       for (int e = 0; e < 8; ++e) {
;         const int idx = tid + e * 512, r = idx >> 6, c = idx & 63;
;         const int oc = t.winmap ? win_orig_col(t.n0 + c) : (t.n0 + c);
;         v[q][e] = oc >= 0 ? t.src[(size_t)(t.k0 + r) * t.ldsrc + oc] : 0.f;
;       }
.LBB0_507:
	v_add_u32_e32 v7, s24, v22
	v_ashrrev_i32_e32 v46, 31, v7
	v_mul_lo_u32 v48, s30, v46
	v_mul_lo_u32 v49, s31, v7
	v_mad_u64_u32 v[46:47], s[2:3], s30, v7, 0
	v_add3_u32 v47, v47, v48, v49
	v_mov_b32_e32 v7, v3
	v_lshl_add_u64 v[46:47], v[46:47], 2, s[28:29]
	v_lshl_add_u64 v[6:7], v[6:7], 2, v[46:47]
	global_load_dword v46, v[6:7], off nt
	s_or_b64 exec, exec, s[0:1]
	s_and_b64 vcc, exec, s[14:15]
	v_mov_b32_e32 v6, v4
	s_cbranch_vccz .LBB0_145

; __device__ __forceinline__ void phase_prep(KP kp, unsigned char* shm) {
;     ...
;       const TTile t = prep_tile(kp, ws, j0 + q);
; #pragma unroll
;       for (int e = 0; e < 8; ++e) {
;         const int idx = tid + e * 512, r = idx >> 6, c = idx & 63;
;         const int oc = t.winmap ? win_orig_col(t.n0 + c) : (t.n0 + c);
;         v[q][e] = oc >= 0 ? t.src[(size_t)(t.k0 + r) * t.ldsrc + oc] : 0.f;
;       }
.LBB0_509:
	v_add_u32_e32 v7, s24, v23
	v_ashrrev_i32_e32 v47, 31, v7
	v_mul_lo_u32 v47, s30, v47
	v_mul_lo_u32 v50, s31, v7
	v_mad_u64_u32 v[48:49], s[2:3], s30, v7, 0
	v_add3_u32 v49, v49, v47, v50
	v_mov_b32_e32 v7, v3
	v_lshl_add_u64 v[48:49], v[48:49], 2, s[28:29]
	v_lshl_add_u64 v[6:7], v[6:7], 2, v[48:49]
	global_load_dword v47, v[6:7], off nt
	s_or_b64 exec, exec, s[0:1]
	s_and_b64 vcc, exec, s[14:15]
	v_mov_b32_e32 v6, v4
	s_cbranch_vccz .LBB0_205

; __device__ __forceinline__ void phase_prep(KP kp, unsigned char* shm) {
;     ...
;       const TTile t = prep_tile(kp, ws, j0 + q);
; #pragma unroll
;       for (int e = 0; e < 8; ++e) {
;         const int idx = tid + e * 512, r = idx >> 6, c = idx & 63;
;         const int oc = t.winmap ? win_orig_col(t.n0 + c) : (t.n0 + c);
;         v[q][e] = oc >= 0 ? t.src[(size_t)(t.k0 + r) * t.ldsrc + oc] : 0.f;
;       }
.LBB0_511:
	v_add_u32_e32 v7, s24, v24
	v_ashrrev_i32_e32 v48, 31, v7
	v_mul_lo_u32 v50, s30, v48
	v_mul_lo_u32 v51, s31, v7
	v_mad_u64_u32 v[48:49], s[2:3], s30, v7, 0
	v_add3_u32 v49, v49, v50, v51
	v_mov_b32_e32 v7, v3
	v_lshl_add_u64 v[48:49], v[48:49], 2, s[28:29]
	v_lshl_add_u64 v[6:7], v[6:7], 2, v[48:49]
	global_load_dword v48, v[6:7], off nt
	s_or_b64 exec, exec, s[0:1]
	s_and_b64 vcc, exec, s[14:15]
	v_mov_b32_e32 v6, v4
	s_cbranch_vccz .LBB0_265

; __device__ __forceinline__ void phase_prep(KP kp, unsigned char* shm) {
;     ...
;       const TTile t = prep_tile(kp, ws, j0 + q);
; #pragma unroll
;       for (int e = 0; e < 8; ++e) {
;         const int idx = tid + e * 512, r = idx >> 6, c = idx & 63;
;         const int oc = t.winmap ? win_orig_col(t.n0 + c) : (t.n0 + c);
;         v[q][e] = oc >= 0 ? t.src[(size_t)(t.k0 + r) * t.ldsrc + oc] : 0.f;
;       }
.LBB0_513:
	v_add_u32_e32 v7, s24, v25
	v_ashrrev_i32_e32 v49, 31, v7
	v_mul_lo_u32 v49, s30, v49
	v_mul_lo_u32 v61, s31, v7
	v_mad_u64_u32 v[50:51], s[2:3], s30, v7, 0
	v_add3_u32 v51, v51, v49, v61
	v_mov_b32_e32 v7, v3
	v_lshl_add_u64 v[50:51], v[50:51], 2, s[28:29]
	v_lshl_add_u64 v[6:7], v[6:7], 2, v[50:51]
	global_load_dword v49, v[6:7], off nt
	s_or_b64 exec, exec, s[0:1]
	s_and_b64 vcc, exec, s[14:15]
	v_mov_b32_e32 v6, v4
	s_cbranch_vccz .LBB0_325

; __device__ __forceinline__ void phase_prep(KP kp, unsigned char* shm) {
;     ...
;       const TTile t = prep_tile(kp, ws, j0 + q);
; #pragma unroll
;       for (int e = 0; e < 8; ++e) {
;         const int idx = tid + e * 512, r = idx >> 6, c = idx & 63;
;         const int oc = t.winmap ? win_orig_col(t.n0 + c) : (t.n0 + c);
;         v[q][e] = oc >= 0 ? t.src[(size_t)(t.k0 + r) * t.ldsrc + oc] : 0.f;
;       }
.LBB0_515:
	v_add_u32_e32 v7, s24, v26
	v_ashrrev_i32_e32 v50, 31, v7
	v_mul_lo_u32 v61, s30, v50
	v_mul_lo_u32 v62, s31, v7
	v_mad_u64_u32 v[50:51], s[2:3], s30, v7, 0
	v_add3_u32 v51, v51, v61, v62
	v_mov_b32_e32 v7, v3
	v_lshl_add_u64 v[50:51], v[50:51], 2, s[28:29]
	v_lshl_add_u64 v[6:7], v[6:7], 2, v[50:51]
	global_load_dword v50, v[6:7], off nt
	s_or_b64 exec, exec, s[0:1]
	s_and_b64 vcc, exec, s[14:15]
	v_mov_b32_e32 v6, v4
	s_cbranch_vccz .LBB0_385

; __device__ __forceinline__ void phase_prep(KP kp, unsigned char* shm) {
;     ...
;       const TTile t = prep_tile(kp, ws, j0 + q);
; #pragma unroll
;       for (int e = 0; e < 8; ++e) {
;         const int idx = tid + e * 512, r = idx >> 6, c = idx & 63;
;         const int oc = t.winmap ? win_orig_col(t.n0 + c) : (t.n0 + c);
;         v[q][e] = oc >= 0 ? t.src[(size_t)(t.k0 + r) * t.ldsrc + oc] : 0.f;
;       }
.LBB0_517:
	v_add_u32_e32 v7, s24, v27
	v_ashrrev_i32_e32 v51, 31, v7
	v_mul_lo_u32 v51, s30, v51
	v_mul_lo_u32 v61, s31, v7
	v_mad_u64_u32 v[62:63], s[2:3], s30, v7, 0
	v_add3_u32 v63, v63, v51, v61
	v_mov_b32_e32 v7, v3
	v_lshl_add_u64 v[62:63], v[62:63], 2, s[28:29]
	v_lshl_add_u64 v[6:7], v[6:7], 2, v[62:63]
	global_load_dword v51, v[6:7], off nt
	s_or_b64 exec, exec, s[0:1]
	s_and_b64 vcc, exec, s[14:15]
	s_cbranch_vccz .LBB0_445

; __device__ __forceinline__ void phase_prep(KP kp, unsigned char* shm) {
;     ...
;       const TTile t = prep_tile(kp, ws, j0 + q);
; #pragma unroll
;       for (int e = 0; e < 8; ++e) {
;         const int idx = tid + e * 512, r = idx >> 6, c = idx & 63;
;         const int oc = t.winmap ? win_orig_col(t.n0 + c) : (t.n0 + c);
;         v[q][e] = oc >= 0 ? t.src[(size_t)(t.k0 + r) * t.ldsrc + oc] : 0.f;
;       }
.LBB0_519:
	v_add_u32_e32 v5, s24, v28
	v_ashrrev_i32_e32 v6, 31, v5
	v_mul_lo_u32 v52, s30, v6
	v_mul_lo_u32 v53, s31, v5
	v_mad_u64_u32 v[6:7], s[2:3], s30, v5, 0
	v_add3_u32 v7, v7, v52, v53
	v_mov_b32_e32 v5, v3
	v_lshl_add_u64 v[6:7], v[6:7], 2, s[28:29]
	v_lshl_add_u64 v[4:5], v[4:5], 2, v[6:7]
	global_load_dword v52, v[4:5], off nt

; __device__ __forceinline__ void phase_prep(KP kp, unsigned char* shm) {
;     ...
;       const TTile t = prep_tile(kp, ws, j0 + q);
; #pragma unroll
;       for (int e = 0; e < 8; ++e) {
;         const int idx = tid + e * 512, r = idx >> 6, c = idx & 63;
;         const int oc = t.winmap ? win_orig_col(t.n0 + c) : (t.n0 + c);
;         v[q][e] = oc >= 0 ? t.src[(size_t)(t.k0 + r) * t.ldsrc + oc] : 0.f;
;       }
.LBB0_1027:
	v_add_u32_e32 v7, s24, v21
	v_ashrrev_i32_e32 v53, 31, v7
	v_mul_lo_u32 v53, s34, v53
	v_mul_lo_u32 v56, s35, v7
	v_mad_u64_u32 v[54:55], s[2:3], s34, v7, 0
	v_add3_u32 v55, v55, v53, v56
	v_mov_b32_e32 v7, v3
	v_lshl_add_u64 v[54:55], v[54:55], 2, s[30:31]
	v_lshl_add_u64 v[6:7], v[6:7], 2, v[54:55]
	global_load_dword v53, v[6:7], off nt
	s_or_b64 exec, exec, s[0:1]
	s_and_b64 vcc, exec, s[14:15]
	v_mov_b32_e32 v6, v4
	s_cbranch_vccz .LBB0_597

; __device__ __forceinline__ void phase_prep(KP kp, unsigned char* shm) {
;     ...
;       const TTile t = prep_tile(kp, ws, j0 + q);
; #pragma unroll
;       for (int e = 0; e < 8; ++e) {
;         const int idx = tid + e * 512, r = idx >> 6, c = idx & 63;
;         const int oc = t.winmap ? win_orig_col(t.n0 + c) : (t.n0 + c);
;         v[q][e] = oc >= 0 ? t.src[(size_t)(t.k0 + r) * t.ldsrc + oc] : 0.f;
;       }
.LBB0_1029:
	v_add_u32_e32 v7, s24, v22
	v_ashrrev_i32_e32 v54, 31, v7
	v_mul_lo_u32 v56, s34, v54
	v_mul_lo_u32 v57, s35, v7
	v_mad_u64_u32 v[54:55], s[2:3], s34, v7, 0
	v_add3_u32 v55, v55, v56, v57
	v_mov_b32_e32 v7, v3
	v_lshl_add_u64 v[54:55], v[54:55], 2, s[30:31]
	v_lshl_add_u64 v[6:7], v[6:7], 2, v[54:55]
	global_load_dword v54, v[6:7], off nt
	s_or_b64 exec, exec, s[0:1]
	s_and_b64 vcc, exec, s[14:15]
	v_mov_b32_e32 v6, v4
	s_cbranch_vccz .LBB0_657

; __device__ __forceinline__ void phase_prep(KP kp, unsigned char* shm) {
;     ...
;       const TTile t = prep_tile(kp, ws, j0 + q);
; #pragma unroll
;       for (int e = 0; e < 8; ++e) {
;         const int idx = tid + e * 512, r = idx >> 6, c = idx & 63;
;         const int oc = t.winmap ? win_orig_col(t.n0 + c) : (t.n0 + c);
;         v[q][e] = oc >= 0 ? t.src[(size_t)(t.k0 + r) * t.ldsrc + oc] : 0.f;
;       }
.LBB0_1031:
	v_add_u32_e32 v7, s24, v23
	v_ashrrev_i32_e32 v55, 31, v7
	v_mul_lo_u32 v55, s34, v55
	v_mul_lo_u32 v58, s35, v7
	v_mad_u64_u32 v[56:57], s[2:3], s34, v7, 0
	v_add3_u32 v57, v57, v55, v58
	v_mov_b32_e32 v7, v3
	v_lshl_add_u64 v[56:57], v[56:57], 2, s[30:31]
	v_lshl_add_u64 v[6:7], v[6:7], 2, v[56:57]
	global_load_dword v55, v[6:7], off nt
	s_or_b64 exec, exec, s[0:1]
	s_and_b64 vcc, exec, s[14:15]
	v_mov_b32_e32 v6, v4
	s_cbranch_vccz .LBB0_717

; __device__ __forceinline__ void phase_prep(KP kp, unsigned char* shm) {
;     ...
;       const TTile t = prep_tile(kp, ws, j0 + q);
; #pragma unroll
;       for (int e = 0; e < 8; ++e) {
;         const int idx = tid + e * 512, r = idx >> 6, c = idx & 63;
;         const int oc = t.winmap ? win_orig_col(t.n0 + c) : (t.n0 + c);
;         v[q][e] = oc >= 0 ? t.src[(size_t)(t.k0 + r) * t.ldsrc + oc] : 0.f;
;       }
.LBB0_1033:
	v_add_u32_e32 v7, s24, v24
	v_ashrrev_i32_e32 v56, 31, v7
	v_mul_lo_u32 v58, s34, v56
	v_mul_lo_u32 v59, s35, v7
	v_mad_u64_u32 v[56:57], s[2:3], s34, v7, 0
	v_add3_u32 v57, v57, v58, v59
	v_mov_b32_e32 v7, v3
	v_lshl_add_u64 v[56:57], v[56:57], 2, s[30:31]
	v_lshl_add_u64 v[6:7], v[6:7], 2, v[56:57]
	global_load_dword v56, v[6:7], off nt
	s_or_b64 exec, exec, s[0:1]
	s_and_b64 vcc, exec, s[14:15]
	v_mov_b32_e32 v6, v4
	s_cbranch_vccz .LBB0_779

; __device__ __forceinline__ void phase_prep(KP kp, unsigned char* shm) {
;     ...
;       const TTile t = prep_tile(kp, ws, j0 + q);
; #pragma unroll
;       for (int e = 0; e < 8; ++e) {
;         const int idx = tid + e * 512, r = idx >> 6, c = idx & 63;
;         const int oc = t.winmap ? win_orig_col(t.n0 + c) : (t.n0 + c);
;         v[q][e] = oc >= 0 ? t.src[(size_t)(t.k0 + r) * t.ldsrc + oc] : 0.f;
;       }
.LBB0_1035:
	v_add_u32_e32 v7, s24, v25
	v_ashrrev_i32_e32 v57, 31, v7
	v_mul_lo_u32 v57, s34, v57
	v_mul_lo_u32 v69, s35, v7
	v_mad_u64_u32 v[58:59], s[2:3], s34, v7, 0
	v_add3_u32 v59, v59, v57, v69
	v_mov_b32_e32 v7, v3
	v_lshl_add_u64 v[58:59], v[58:59], 2, s[30:31]
	v_lshl_add_u64 v[6:7], v[6:7], 2, v[58:59]
	global_load_dword v57, v[6:7], off nt
	s_or_b64 exec, exec, s[0:1]
	s_and_b64 vcc, exec, s[14:15]
	v_mov_b32_e32 v6, v4
	s_cbranch_vccz .LBB0_841

; __device__ __forceinline__ void phase_prep(KP kp, unsigned char* shm) {
;     ...
;       const TTile t = prep_tile(kp, ws, j0 + q);
; #pragma unroll
;       for (int e = 0; e < 8; ++e) {
;         const int idx = tid + e * 512, r = idx >> 6, c = idx & 63;
;         const int oc = t.winmap ? win_orig_col(t.n0 + c) : (t.n0 + c);
;         v[q][e] = oc >= 0 ? t.src[(size_t)(t.k0 + r) * t.ldsrc + oc] : 0.f;
;       }
.LBB0_1037:
	v_add_u32_e32 v7, s24, v26
	v_ashrrev_i32_e32 v58, 31, v7
	v_mul_lo_u32 v69, s34, v58
	v_mul_lo_u32 v70, s35, v7
	v_mad_u64_u32 v[58:59], s[2:3], s34, v7, 0
	v_add3_u32 v59, v59, v69, v70
	v_mov_b32_e32 v7, v3
	v_lshl_add_u64 v[58:59], v[58:59], 2, s[30:31]
	v_lshl_add_u64 v[6:7], v[6:7], 2, v[58:59]
	global_load_dword v58, v[6:7], off nt
	s_or_b64 exec, exec, s[0:1]
	s_and_b64 vcc, exec, s[14:15]
	v_mov_b32_e32 v6, v4
	s_cbranch_vccz .LBB0_903

; __device__ __forceinline__ void phase_prep(KP kp, unsigned char* shm) {
;     ...
;       const TTile t = prep_tile(kp, ws, j0 + q);
; #pragma unroll
;       for (int e = 0; e < 8; ++e) {
;         const int idx = tid + e * 512, r = idx >> 6, c = idx & 63;
;         const int oc = t.winmap ? win_orig_col(t.n0 + c) : (t.n0 + c);
;         v[q][e] = oc >= 0 ? t.src[(size_t)(t.k0 + r) * t.ldsrc + oc] : 0.f;
;       }
.LBB0_1039:
	v_add_u32_e32 v7, s24, v27
	v_ashrrev_i32_e32 v59, 31, v7
	v_mul_lo_u32 v59, s34, v59
	v_mul_lo_u32 v69, s35, v7
	v_mad_u64_u32 v[70:71], s[2:3], s34, v7, 0
	v_add3_u32 v71, v71, v59, v69
	v_mov_b32_e32 v7, v3
	v_lshl_add_u64 v[70:71], v[70:71], 2, s[30:31]
	v_lshl_add_u64 v[6:7], v[6:7], 2, v[70:71]
	global_load_dword v59, v[6:7], off nt
	s_or_b64 exec, exec, s[0:1]
	s_and_b64 vcc, exec, s[14:15]
	s_cbranch_vccz .LBB0_965

; __device__ __forceinline__ void phase_prep(KP kp, unsigned char* shm) {
;     ...
;       const TTile t = prep_tile(kp, ws, j0 + q);
; #pragma unroll
;       for (int e = 0; e < 8; ++e) {
;         const int idx = tid + e * 512, r = idx >> 6, c = idx & 63;
;         const int oc = t.winmap ? win_orig_col(t.n0 + c) : (t.n0 + c);
;         v[q][e] = oc >= 0 ? t.src[(size_t)(t.k0 + r) * t.ldsrc + oc] : 0.f;
;       }
.LBB0_1041:
	v_add_u32_e32 v5, s24, v28
	v_ashrrev_i32_e32 v6, 31, v5
	v_mul_lo_u32 v60, s34, v6
	v_mul_lo_u32 v61, s35, v5
	v_mad_u64_u32 v[6:7], s[2:3], s34, v5, 0
	v_add3_u32 v7, v7, v60, v61
	v_mov_b32_e32 v5, v3
	v_lshl_add_u64 v[6:7], v[6:7], 2, s[30:31]
	v_lshl_add_u64 v[4:5], v[4:5], 2, v[6:7]
	global_load_dword v60, v[4:5], off nt

; __device__ __forceinline__ void phase_prep(KP kp, unsigned char* shm) {
;     ...
;       const TTile t = prep_tile(kp, ws, j0 + q);
; #pragma unroll
;       for (int e = 0; e < 8; ++e) {
;         const int idx = tid + e * 512, r = idx >> 6, c = idx & 63;
;         const int oc = t.winmap ? win_orig_col(t.n0 + c) : (t.n0 + c);
;         v[q][e] = oc >= 0 ? t.src[(size_t)(t.k0 + r) * t.ldsrc + oc] : 0.f;
;       }
.LBB0_1549:
	v_add_u32_e32 v7, s24, v21
	v_ashrrev_i32_e32 v61, 31, v7
	v_mul_lo_u32 v61, s36, v61
	v_mul_lo_u32 v64, s37, v7
	v_mad_u64_u32 v[62:63], s[2:3], s36, v7, 0
	v_add3_u32 v63, v63, v61, v64
	v_mov_b32_e32 v7, v3
	v_lshl_add_u64 v[62:63], v[62:63], 2, s[34:35]
	v_lshl_add_u64 v[6:7], v[6:7], 2, v[62:63]
	global_load_dword v61, v[6:7], off nt
	s_or_b64 exec, exec, s[0:1]
	s_and_b64 vcc, exec, s[14:15]
	v_mov_b32_e32 v6, v4
	s_cbranch_vccz .LBB0_1119

; __device__ __forceinline__ void phase_prep(KP kp, unsigned char* shm) {
;     ...
;       const TTile t = prep_tile(kp, ws, j0 + q);
; #pragma unroll
;       for (int e = 0; e < 8; ++e) {
;         const int idx = tid + e * 512, r = idx >> 6, c = idx & 63;
;         const int oc = t.winmap ? win_orig_col(t.n0 + c) : (t.n0 + c);
;         v[q][e] = oc >= 0 ? t.src[(size_t)(t.k0 + r) * t.ldsrc + oc] : 0.f;
;       }
.LBB0_1551:
	v_add_u32_e32 v7, s24, v22
	v_ashrrev_i32_e32 v62, 31, v7
	v_mul_lo_u32 v64, s36, v62
	v_mul_lo_u32 v65, s37, v7
	v_mad_u64_u32 v[62:63], s[2:3], s36, v7, 0
	v_add3_u32 v63, v63, v64, v65
	v_mov_b32_e32 v7, v3
	v_lshl_add_u64 v[62:63], v[62:63], 2, s[34:35]
	v_lshl_add_u64 v[6:7], v[6:7], 2, v[62:63]
	global_load_dword v62, v[6:7], off nt
	s_or_b64 exec, exec, s[0:1]
	s_and_b64 vcc, exec, s[14:15]
	v_mov_b32_e32 v6, v4
	s_cbranch_vccz .LBB0_1179

; __device__ __forceinline__ void phase_prep(KP kp, unsigned char* shm) {
;     ...
;       const TTile t = prep_tile(kp, ws, j0 + q);
; #pragma unroll
;       for (int e = 0; e < 8; ++e) {
;         const int idx = tid + e * 512, r = idx >> 6, c = idx & 63;
;         const int oc = t.winmap ? win_orig_col(t.n0 + c) : (t.n0 + c);
;         v[q][e] = oc >= 0 ? t.src[(size_t)(t.k0 + r) * t.ldsrc + oc] : 0.f;
;       }
.LBB0_1553:
	v_add_u32_e32 v7, s24, v23
	v_ashrrev_i32_e32 v63, 31, v7
	v_mul_lo_u32 v63, s36, v63
	v_mul_lo_u32 v66, s37, v7
	v_mad_u64_u32 v[64:65], s[2:3], s36, v7, 0
	v_add3_u32 v65, v65, v63, v66
	v_mov_b32_e32 v7, v3
	v_lshl_add_u64 v[64:65], v[64:65], 2, s[34:35]
	v_lshl_add_u64 v[6:7], v[6:7], 2, v[64:65]
	global_load_dword v63, v[6:7], off nt
	s_or_b64 exec, exec, s[0:1]
	s_and_b64 vcc, exec, s[14:15]
	v_mov_b32_e32 v6, v4
	s_cbranch_vccz .LBB0_1239

; __device__ __forceinline__ void phase_prep(KP kp, unsigned char* shm) {
;     ...
;       const TTile t = prep_tile(kp, ws, j0 + q);
; #pragma unroll
;       for (int e = 0; e < 8; ++e) {
;         const int idx = tid + e * 512, r = idx >> 6, c = idx & 63;
;         const int oc = t.winmap ? win_orig_col(t.n0 + c) : (t.n0 + c);
;         v[q][e] = oc >= 0 ? t.src[(size_t)(t.k0 + r) * t.ldsrc + oc] : 0.f;
;       }
.LBB0_1555:
	v_add_u32_e32 v7, s24, v24
	v_ashrrev_i32_e32 v64, 31, v7
	v_mul_lo_u32 v66, s36, v64
	v_mul_lo_u32 v67, s37, v7
	v_mad_u64_u32 v[64:65], s[2:3], s36, v7, 0
	v_add3_u32 v65, v65, v66, v67
	v_mov_b32_e32 v7, v3
	v_lshl_add_u64 v[64:65], v[64:65], 2, s[34:35]
	v_lshl_add_u64 v[6:7], v[6:7], 2, v[64:65]
	global_load_dword v64, v[6:7], off nt
	s_or_b64 exec, exec, s[0:1]
	s_and_b64 vcc, exec, s[14:15]
	v_mov_b32_e32 v6, v4
	s_cbranch_vccz .LBB0_1301

; __device__ __forceinline__ void phase_prep(KP kp, unsigned char* shm) {
;     ...
;       const TTile t = prep_tile(kp, ws, j0 + q);
; #pragma unroll
;       for (int e = 0; e < 8; ++e) {
;         const int idx = tid + e * 512, r = idx >> 6, c = idx & 63;
;         const int oc = t.winmap ? win_orig_col(t.n0 + c) : (t.n0 + c);
;         v[q][e] = oc >= 0 ? t.src[(size_t)(t.k0 + r) * t.ldsrc + oc] : 0.f;
;       }
.LBB0_1557:
	v_add_u32_e32 v7, s24, v25
	v_ashrrev_i32_e32 v65, 31, v7
	v_mul_lo_u32 v65, s36, v65
	v_mul_lo_u32 v77, s37, v7
	v_mad_u64_u32 v[66:67], s[2:3], s36, v7, 0
	v_add3_u32 v67, v67, v65, v77
	v_mov_b32_e32 v7, v3
	v_lshl_add_u64 v[66:67], v[66:67], 2, s[34:35]
	v_lshl_add_u64 v[6:7], v[6:7], 2, v[66:67]
	global_load_dword v65, v[6:7], off nt
	s_or_b64 exec, exec, s[0:1]
	s_and_b64 vcc, exec, s[14:15]
	v_mov_b32_e32 v6, v4
	s_cbranch_vccz .LBB0_1363

; __device__ __forceinline__ void phase_prep(KP kp, unsigned char* shm) {
;     ...
;       const TTile t = prep_tile(kp, ws, j0 + q);
; #pragma unroll
;       for (int e = 0; e < 8; ++e) {
;         const int idx = tid + e * 512, r = idx >> 6, c = idx & 63;
;         const int oc = t.winmap ? win_orig_col(t.n0 + c) : (t.n0 + c);
;         v[q][e] = oc >= 0 ? t.src[(size_t)(t.k0 + r) * t.ldsrc + oc] : 0.f;
;       }
.LBB0_1559:
	v_add_u32_e32 v7, s24, v26
	v_ashrrev_i32_e32 v66, 31, v7
	v_mul_lo_u32 v77, s36, v66
	v_mul_lo_u32 v78, s37, v7
	v_mad_u64_u32 v[66:67], s[2:3], s36, v7, 0
	v_add3_u32 v67, v67, v77, v78
	v_mov_b32_e32 v7, v3
	v_lshl_add_u64 v[66:67], v[66:67], 2, s[34:35]
	v_lshl_add_u64 v[6:7], v[6:7], 2, v[66:67]
	global_load_dword v66, v[6:7], off nt
	s_or_b64 exec, exec, s[0:1]
	s_and_b64 vcc, exec, s[14:15]
	v_mov_b32_e32 v6, v4
	s_cbranch_vccz .LBB0_1425

; __device__ __forceinline__ void phase_prep(KP kp, unsigned char* shm) {
;     ...
;       const TTile t = prep_tile(kp, ws, j0 + q);
; #pragma unroll
;       for (int e = 0; e < 8; ++e) {
;         const int idx = tid + e * 512, r = idx >> 6, c = idx & 63;
;         const int oc = t.winmap ? win_orig_col(t.n0 + c) : (t.n0 + c);
;         v[q][e] = oc >= 0 ? t.src[(size_t)(t.k0 + r) * t.ldsrc + oc] : 0.f;
;       }
.LBB0_1561:
	v_add_u32_e32 v7, s24, v27
	v_ashrrev_i32_e32 v67, 31, v7
	v_mul_lo_u32 v67, s36, v67
	v_mul_lo_u32 v77, s37, v7
	v_mad_u64_u32 v[78:79], s[2:3], s36, v7, 0
	v_add3_u32 v79, v79, v67, v77
	v_mov_b32_e32 v7, v3
	v_lshl_add_u64 v[78:79], v[78:79], 2, s[34:35]
	v_lshl_add_u64 v[6:7], v[6:7], 2, v[78:79]
	global_load_dword v67, v[6:7], off nt
	s_or_b64 exec, exec, s[0:1]
	s_and_b64 vcc, exec, s[14:15]
	s_cbranch_vccz .LBB0_1487

; __device__ __forceinline__ void phase_prep(KP kp, unsigned char* shm) {
;     ...
;       const TTile t = prep_tile(kp, ws, j0 + q);
; #pragma unroll
;       for (int e = 0; e < 8; ++e) {
;         const int idx = tid + e * 512, r = idx >> 6, c = idx & 63;
;         const int oc = t.winmap ? win_orig_col(t.n0 + c) : (t.n0 + c);
;         v[q][e] = oc >= 0 ? t.src[(size_t)(t.k0 + r) * t.ldsrc + oc] : 0.f;
;       }
.LBB0_1563:
	v_add_u32_e32 v5, s24, v28
	v_ashrrev_i32_e32 v6, 31, v5
	v_mul_lo_u32 v68, s36, v6
	v_mul_lo_u32 v69, s37, v5
	v_mad_u64_u32 v[6:7], s[2:3], s36, v5, 0
	v_add3_u32 v7, v7, v68, v69
	v_mov_b32_e32 v5, v3
	v_lshl_add_u64 v[6:7], v[6:7], 2, s[34:35]
	v_lshl_add_u64 v[4:5], v[4:5], 2, v[6:7]
	global_load_dword v68, v[4:5], off nt

; __device__ __forceinline__ void phase_prep(KP kp, unsigned char* shm) {
;     ...
;       const TTile t = prep_tile(kp, ws, j0 + q);
; #pragma unroll
;       for (int e = 0; e < 8; ++e) {
;         const int idx = tid + e * 512, r = idx >> 6, c = idx & 63;
;         const int oc = t.winmap ? win_orig_col(t.n0 + c) : (t.n0 + c);
;         v[q][e] = oc >= 0 ? t.src[(size_t)(t.k0 + r) * t.ldsrc + oc] : 0.f;
;       }
.LBB0_2071:
	v_add_u32_e32 v7, s24, v21
	v_ashrrev_i32_e32 v76, 31, v7
	v_mul_lo_u32 v76, s38, v76
	v_mul_lo_u32 v79, s39, v7
	v_mad_u64_u32 v[80:81], s[2:3], s38, v7, 0
	v_add3_u32 v81, v81, v76, v79
	v_mov_b32_e32 v7, v3
	v_lshl_add_u64 v[80:81], v[80:81], 2, s[36:37]
	v_lshl_add_u64 v[6:7], v[6:7], 2, v[80:81]
	global_load_dword v76, v[6:7], off nt
	s_or_b64 exec, exec, s[0:1]
	s_and_b64 vcc, exec, s[14:15]
	v_mov_b32_e32 v6, v4
	s_cbranch_vccz .LBB0_1641

; __device__ __forceinline__ void phase_prep(KP kp, unsigned char* shm) {
;     ...
;       const TTile t = prep_tile(kp, ws, j0 + q);
; #pragma unroll
;       for (int e = 0; e < 8; ++e) {
;         const int idx = tid + e * 512, r = idx >> 6, c = idx & 63;
;         const int oc = t.winmap ? win_orig_col(t.n0 + c) : (t.n0 + c);
;         v[q][e] = oc >= 0 ? t.src[(size_t)(t.k0 + r) * t.ldsrc + oc] : 0.f;
;       }
.LBB0_2073:
	v_add_u32_e32 v7, s24, v22
	v_ashrrev_i32_e32 v79, 31, v7
	v_mul_lo_u32 v79, s38, v79
	v_mul_lo_u32 v82, s39, v7
	v_mad_u64_u32 v[80:81], s[2:3], s38, v7, 0
	v_add3_u32 v81, v81, v79, v82
	v_mov_b32_e32 v7, v3
	v_lshl_add_u64 v[80:81], v[80:81], 2, s[36:37]
	v_lshl_add_u64 v[6:7], v[6:7], 2, v[80:81]
	global_load_dword v79, v[6:7], off nt
	s_or_b64 exec, exec, s[0:1]
	s_and_b64 vcc, exec, s[14:15]
	v_mov_b32_e32 v6, v4
	s_cbranch_vccz .LBB0_1701

; __device__ __forceinline__ void phase_prep(KP kp, unsigned char* shm) {
;     ...
;       const TTile t = prep_tile(kp, ws, j0 + q);
; #pragma unroll
;       for (int e = 0; e < 8; ++e) {
;         const int idx = tid + e * 512, r = idx >> 6, c = idx & 63;
;         const int oc = t.winmap ? win_orig_col(t.n0 + c) : (t.n0 + c);
;         v[q][e] = oc >= 0 ? t.src[(size_t)(t.k0 + r) * t.ldsrc + oc] : 0.f;
;       }
.LBB0_2075:
	v_add_u32_e32 v7, s24, v23
	v_ashrrev_i32_e32 v80, 31, v7
	v_mul_lo_u32 v82, s38, v80
	v_mul_lo_u32 v83, s39, v7
	v_mad_u64_u32 v[80:81], s[2:3], s38, v7, 0
	v_add3_u32 v81, v81, v82, v83
	v_mov_b32_e32 v7, v3
	v_lshl_add_u64 v[80:81], v[80:81], 2, s[36:37]
	v_lshl_add_u64 v[6:7], v[6:7], 2, v[80:81]
	global_load_dword v80, v[6:7], off nt
	s_or_b64 exec, exec, s[0:1]
	s_and_b64 vcc, exec, s[14:15]
	v_mov_b32_e32 v6, v4
	s_cbranch_vccz .LBB0_1761

; __device__ __forceinline__ void phase_prep(KP kp, unsigned char* shm) {
;     ...
;       const TTile t = prep_tile(kp, ws, j0 + q);
; #pragma unroll
;       for (int e = 0; e < 8; ++e) {
;         const int idx = tid + e * 512, r = idx >> 6, c = idx & 63;
;         const int oc = t.winmap ? win_orig_col(t.n0 + c) : (t.n0 + c);
;         v[q][e] = oc >= 0 ? t.src[(size_t)(t.k0 + r) * t.ldsrc + oc] : 0.f;
;       }
.LBB0_2077:
	v_add_u32_e32 v7, s24, v24
	v_ashrrev_i32_e32 v81, 31, v7
	v_mul_lo_u32 v81, s38, v81
	v_mul_lo_u32 v84, s39, v7
	v_mad_u64_u32 v[82:83], s[2:3], s38, v7, 0
	v_add3_u32 v83, v83, v81, v84
	v_mov_b32_e32 v7, v3
	v_lshl_add_u64 v[82:83], v[82:83], 2, s[36:37]
	v_lshl_add_u64 v[6:7], v[6:7], 2, v[82:83]
	global_load_dword v81, v[6:7], off nt
	s_or_b64 exec, exec, s[0:1]
	s_and_b64 vcc, exec, s[14:15]
	v_mov_b32_e32 v6, v4
	s_cbranch_vccz .LBB0_1823

; __device__ __forceinline__ void phase_prep(KP kp, unsigned char* shm) {
;     ...
;       const TTile t = prep_tile(kp, ws, j0 + q);
; #pragma unroll
;       for (int e = 0; e < 8; ++e) {
;         const int idx = tid + e * 512, r = idx >> 6, c = idx & 63;
;         const int oc = t.winmap ? win_orig_col(t.n0 + c) : (t.n0 + c);
;         v[q][e] = oc >= 0 ? t.src[(size_t)(t.k0 + r) * t.ldsrc + oc] : 0.f;
;       }
.LBB0_2079:
	v_add_u32_e32 v7, s24, v25
	v_ashrrev_i32_e32 v82, 31, v7
	v_mul_lo_u32 v84, s38, v82
	v_mul_lo_u32 v85, s39, v7
	v_mad_u64_u32 v[82:83], s[2:3], s38, v7, 0
	v_add3_u32 v83, v83, v84, v85
	v_mov_b32_e32 v7, v3
	v_lshl_add_u64 v[82:83], v[82:83], 2, s[36:37]
	v_lshl_add_u64 v[6:7], v[6:7], 2, v[82:83]
	global_load_dword v82, v[6:7], off nt
	s_or_b64 exec, exec, s[0:1]
	s_and_b64 vcc, exec, s[14:15]
	v_mov_b32_e32 v6, v4
	s_cbranch_vccz .LBB0_1885

; __device__ __forceinline__ void phase_prep(KP kp, unsigned char* shm) {
;     ...
;       const TTile t = prep_tile(kp, ws, j0 + q);
; #pragma unroll
;       for (int e = 0; e < 8; ++e) {
;         const int idx = tid + e * 512, r = idx >> 6, c = idx & 63;
;         const int oc = t.winmap ? win_orig_col(t.n0 + c) : (t.n0 + c);
;         v[q][e] = oc >= 0 ? t.src[(size_t)(t.k0 + r) * t.ldsrc + oc] : 0.f;
;       }
.LBB0_2081:
	v_add_u32_e32 v7, s24, v26
	v_ashrrev_i32_e32 v83, 31, v7
	v_mul_lo_u32 v83, s38, v83
	v_mul_lo_u32 v86, s39, v7
	v_mad_u64_u32 v[84:85], s[2:3], s38, v7, 0
	v_add3_u32 v85, v85, v83, v86
	v_mov_b32_e32 v7, v3
	v_lshl_add_u64 v[84:85], v[84:85], 2, s[36:37]
	v_lshl_add_u64 v[6:7], v[6:7], 2, v[84:85]
	global_load_dword v83, v[6:7], off nt
	s_or_b64 exec, exec, s[0:1]
	s_and_b64 vcc, exec, s[14:15]
	v_mov_b32_e32 v6, v4
	s_cbranch_vccz .LBB0_1947

; __device__ __forceinline__ void phase_prep(KP kp, unsigned char* shm) {
;     ...
;       const TTile t = prep_tile(kp, ws, j0 + q);
; #pragma unroll
;       for (int e = 0; e < 8; ++e) {
;         const int idx = tid + e * 512, r = idx >> 6, c = idx & 63;
;         const int oc = t.winmap ? win_orig_col(t.n0 + c) : (t.n0 + c);
;         v[q][e] = oc >= 0 ? t.src[(size_t)(t.k0 + r) * t.ldsrc + oc] : 0.f;
;       }
.LBB0_2083:
	v_add_u32_e32 v7, s24, v27
	v_ashrrev_i32_e32 v84, 31, v7
	v_mul_lo_u32 v86, s38, v84
	v_mul_lo_u32 v87, s39, v7
	v_mad_u64_u32 v[84:85], s[2:3], s38, v7, 0
	v_add3_u32 v85, v85, v86, v87
	v_mov_b32_e32 v7, v3
	v_lshl_add_u64 v[84:85], v[84:85], 2, s[36:37]
	v_lshl_add_u64 v[6:7], v[6:7], 2, v[84:85]
	global_load_dword v7, v[6:7], off nt
	s_or_b64 exec, exec, s[0:1]
	s_and_b64 vcc, exec, s[14:15]
	s_cbranch_vccz .LBB0_2009

; __device__ __forceinline__ void phase_prep(KP kp, unsigned char* shm) {
;     ...
;       const TTile t = prep_tile(kp, ws, j0 + q);
; #pragma unroll
;       for (int e = 0; e < 8; ++e) {
;         const int idx = tid + e * 512, r = idx >> 6, c = idx & 63;
;         const int oc = t.winmap ? win_orig_col(t.n0 + c) : (t.n0 + c);
;         v[q][e] = oc >= 0 ? t.src[(size_t)(t.k0 + r) * t.ldsrc + oc] : 0.f;
;       }
.LBB0_2085:
	v_add_u32_e32 v5, s24, v28
	v_ashrrev_i32_e32 v6, 31, v5
	v_mul_lo_u32 v6, s38, v6
	v_mul_lo_u32 v69, s39, v5
	v_mad_u64_u32 v[70:71], s[2:3], s38, v5, 0
	v_add3_u32 v71, v71, v6, v69
	v_mov_b32_e32 v5, v3
	v_lshl_add_u64 v[70:71], v[70:71], 2, s[36:37]
	v_lshl_add_u64 v[4:5], v[4:5], 2, v[70:71]
	global_load_dword v5, v[4:5], off nt

; __device__ __forceinline__ void cvt_rows(const float* __restrict__ src, bf16_t* __restrict__ dst, size_t n4, size_t gtid, size_t gn) {
;   for (size_t i0 = gtid; i0 < n4; i0 += 4 * gn) {
;     f32x4 v[4];
; #pragma unroll
;     for (int q = 0; q < 4; ++q) { const size_t i = i0 + q * gn; v[q] = i < n4 ? *(const f32x4*)(src + i * 4) : (f32x4){0.f, 0.f, 0.f, 0.f}; }
.LBB0_2223:
	v_lshl_add_u64 v[2:3], s[14:15], 0, v[20:21]
	global_load_dwordx4 v[10:13], v[2:3], off nt
	v_lshl_add_u64 v[28:29], v[14:15], 0, s[8:9]
	v_cmp_gt_u64_e32 vcc, s[4:5], v[28:29]
	v_mov_b32_e32 v2, 0
	v_mov_b32_e32 v6, 0
	v_mov_b32_e32 v7, 0
	v_mov_b32_e32 v8, 0
	v_mov_b32_e32 v9, 0
	s_and_saveexec_b64 s[0:1], vcc
	s_cbranch_execz .LBB0_2225
	v_lshl_add_u64 v[4:5], s[34:35], 0, v[20:21]
	global_load_dwordx4 v[6:9], v[4:5], off nt
.LBB0_2225:
	s_or_b64 exec, exec, s[0:1]
	v_lshl_add_u64 v[4:5], s[24:25], 0, v[14:15]
	v_cmp_gt_u64_e64 s[0:1], s[4:5], v[4:5]
	v_mov_b32_e32 v3, 0
	v_mov_b32_e32 v4, 0
	v_mov_b32_e32 v5, 0
	s_and_saveexec_b64 s[2:3], s[0:1]
	s_cbranch_execz .LBB0_2227
	v_lshl_add_u64 v[2:3], s[26:27], 0, v[20:21]
	global_load_dwordx4 v[2:5], v[2:3], off nt
.LBB0_2227:
	s_or_b64 exec, exec, s[2:3]
	v_lshl_add_u64 v[14:15], s[10:11], 0, v[14:15]
	v_cmp_gt_u64_e64 s[2:3], s[4:5], v[14:15]
	v_mov_b32_e32 v14, 0
	v_mov_b32_e32 v15, 0
	v_mov_b32_e32 v16, 0
	v_mov_b32_e32 v17, 0
	s_and_saveexec_b64 s[42:43], s[2:3]
	s_cbranch_execz .LBB0_2229
	v_lshl_add_u64 v[14:15], s[30:31], 0, v[20:21]
	global_load_dwordx4 v[14:17], v[14:15], off nt

; __device__ __forceinline__ void cvt_rows(const float* __restrict__ src, bf16_t* __restrict__ dst, size_t n4, size_t gtid, size_t gn) {
;   for (size_t i0 = gtid; i0 < n4; i0 += 4 * gn) {
;     f32x4 v[4];
; #pragma unroll
;     for (int q = 0; q < 4; ++q) { const size_t i = i0 + q * gn; v[q] = i < n4 ? *(const f32x4*)(src + i * 4) : (f32x4){0.f, 0.f, 0.f, 0.f}; }
.LBB0_2238:
	v_lshl_add_u64 v[2:3], s[14:15], 0, v[28:29]
	global_load_dwordx4 v[10:13], v[2:3], off nt
	v_lshl_add_u64 v[30:31], v[14:15], 0, s[8:9]
	v_cmp_gt_u64_e64 s[0:1], s[16:17], v[30:31]
	v_mov_b32_e32 v2, 0
	v_mov_b32_e32 v6, 0
	v_mov_b32_e32 v7, 0
	v_mov_b32_e32 v8, 0
	v_mov_b32_e32 v9, 0
	s_and_saveexec_b64 s[2:3], s[0:1]
	s_cbranch_execz .LBB0_2240
	v_lshl_add_u64 v[4:5], s[38:39], 0, v[28:29]
	global_load_dwordx4 v[6:9], v[4:5], off nt
.LBB0_2240:
	s_or_b64 exec, exec, s[2:3]
	v_lshl_add_u64 v[4:5], s[28:29], 0, v[14:15]
	v_cmp_gt_u64_e64 s[2:3], s[16:17], v[4:5]
	v_mov_b32_e32 v3, 0
	v_mov_b32_e32 v4, 0
	v_mov_b32_e32 v5, 0
	s_and_saveexec_b64 s[4:5], s[2:3]
	s_cbranch_execz .LBB0_2242
	v_lshl_add_u64 v[2:3], s[30:31], 0, v[28:29]
	global_load_dwordx4 v[2:5], v[2:3], off nt
.LBB0_2242:
	s_or_b64 exec, exec, s[4:5]
	v_lshl_add_u64 v[14:15], s[10:11], 0, v[14:15]
	v_cmp_gt_u64_e64 s[4:5], s[16:17], v[14:15]
	v_mov_b32_e32 v14, 0
	v_mov_b32_e32 v15, 0
	v_mov_b32_e32 v16, 0
	v_mov_b32_e32 v17, 0
	s_and_saveexec_b64 s[46:47], s[4:5]
	s_cbranch_execz .LBB0_2244
	v_lshl_add_u64 v[14:15], s[36:37], 0, v[28:29]
	global_load_dwordx4 v[14:17], v[14:15], off nt

; __device__ __forceinline__ void phase_prep(KP kp, unsigned char* shm) {
;     ...
;   for (size_t i = gtid; i < (size_t)MS * 256; i += gn)
;     *(f32x4*)(kp->out + O_Y + (size_t)MP * 1024 + i * 4) = *(const f32x4*)(kp->x_sample + i * 4) * ALPHA;
.LBB0_2251:
	v_lshl_add_u64 v[4:5], s[14:15], 0, v[18:19]
	global_load_dwordx4 v[4:7], v[4:5], off nt
	v_lshl_add_u64 v[2:3], v[2:3], 0, s[8:9]
	v_cmp_lt_u64_e64 s[0:1], s[16:17], v[2:3]
	v_lshl_add_u64 v[8:9], s[26:27], 0, v[18:19]
	v_lshl_add_u64 v[18:19], v[18:19], 0, s[24:25]
	s_or_b64 s[2:3], s[0:1], s[2:3]
	s_waitcnt vmcnt(0)
	v_pk_mul_f32 v[4:5], v[4:5], s[4:5] op_sel_hi:[1,0]
	v_pk_mul_f32 v[6:7], v[6:7], s[4:5] op_sel_hi:[1,0]
	global_store_dwordx4 v[8:9], v[4:7], off
	s_andn2_b64 exec, exec, s[2:3]
	s_cbranch_execnz .LBB0_2251

; __device__ __forceinline__ void phase_prep(KP kp, unsigned char* shm) {
;     ...
;   for (size_t i0 = gtid; i0 < 2ull * 16 * 2048 * 32; i0 += 4 * gn) {
;     f32x4 a[4], b[4];
; #pragma unroll
;     for (int q = 0; q < 4; ++q) {
;       const size_t i = i0 + q * gn;
;       const bool ok = i < 2ull * 16 * 2048 * 32;
;       a[q] = ok ? *(const f32x4*)(kp->cache_k + i * 4) : (f32x4){0.f, 0.f, 0.f, 0.f};
;       b[q] = ok ? *(const f32x4*)(kp->cache_v + i * 4) : (f32x4){0.f, 0.f, 0.f, 0.f};
;     }
.LBB0_2255:
	v_lshl_add_u64 v[2:3], v[54:55], 0, s[38:39]
	global_load_dwordx4 v[14:17], v[2:3], off nt
	v_lshl_add_u64 v[2:3], v[52:53], 0, s[38:39]
	global_load_dwordx4 v[2:5], v[2:3], off nt
	v_lshl_add_u64 v[58:59], v[60:61], 0, s[8:9]
	v_cmp_gt_u64_e64 s[0:1], s[12:13], v[58:59]
	v_cmp_lt_u64_e64 s[2:3], s[36:37], v[58:59]
	s_and_saveexec_b64 s[4:5], s[2:3]
	s_xor_b64 s[2:3], exec, s[4:5]
	s_or_saveexec_b64 s[2:3], s[2:3]
	v_mov_b32_e32 v10, 0
	v_mov_b32_e32 v11, 0
	v_mov_b32_e32 v12, 0
	v_mov_b32_e32 v13, 0
	v_mov_b32_e32 v6, 0
	v_mov_b32_e32 v7, 0
	v_mov_b32_e32 v8, 0
	v_mov_b32_e32 v9, 0
	s_xor_b64 exec, exec, s[2:3]
	s_cbranch_execz .LBB0_2257
	v_lshl_add_u64 v[6:7], v[50:51], 0, s[38:39]
	global_load_dwordx4 v[10:13], v[6:7], off nt
	v_lshl_add_u64 v[6:7], v[48:49], 0, s[38:39]
	global_load_dwordx4 v[6:9], v[6:7], off nt
.LBB0_2257:
	s_or_b64 exec, exec, s[2:3]
	v_lshl_add_u64 v[62:63], s[28:29], 0, v[60:61]
	v_cmp_gt_u64_e64 s[2:3], s[12:13], v[62:63]
	v_cmp_lt_u64_e64 s[4:5], s[36:37], v[62:63]
	s_and_saveexec_b64 s[6:7], s[4:5]
	s_xor_b64 s[4:5], exec, s[6:7]
	s_or_saveexec_b64 s[4:5], s[4:5]
	v_mov_b32_e32 v22, 0
	v_mov_b32_e32 v23, 0
	v_mov_b32_e32 v24, 0
	v_mov_b32_e32 v25, 0
	v_mov_b32_e32 v18, 0
	v_mov_b32_e32 v19, 0
	v_mov_b32_e32 v20, 0
	v_mov_b32_e32 v21, 0
	s_xor_b64 exec, exec, s[4:5]
	s_cbranch_execz .LBB0_2259
	v_lshl_add_u64 v[18:19], v[42:43], 0, s[38:39]
	global_load_dwordx4 v[22:25], v[18:19], off nt
	v_lshl_add_u64 v[18:19], v[40:41], 0, s[38:39]
	global_load_dwordx4 v[18:21], v[18:19], off nt
.LBB0_2259:
	s_or_b64 exec, exec, s[4:5]
	v_lshl_add_u64 v[64:65], s[10:11], 0, v[60:61]
	v_cmp_gt_u64_e64 s[4:5], s[12:13], v[64:65]
	v_cmp_lt_u64_e64 s[6:7], s[36:37], v[64:65]
	s_and_saveexec_b64 s[42:43], s[6:7]
	s_xor_b64 s[6:7], exec, s[42:43]
	s_or_saveexec_b64 s[6:7], s[6:7]
	v_mov_b32_e32 v30, 0
	v_mov_b32_e32 v31, 0
	v_mov_b32_e32 v32, 0
	v_mov_b32_e32 v33, 0
	v_mov_b32_e32 v26, 0
	v_mov_b32_e32 v27, 0
	v_mov_b32_e32 v28, 0
	v_mov_b32_e32 v29, 0
	s_xor_b64 exec, exec, s[6:7]
	s_cbranch_execz .LBB0_2261
	v_lshl_add_u64 v[26:27], v[46:47], 0, s[38:39]
	global_load_dwordx4 v[30:33], v[26:27], off nt
	v_lshl_add_u64 v[26:27], v[44:45], 0, s[38:39]
	global_load_dwordx4 v[26:29], v[26:27], off nt

; __device__ __forceinline__ void phase_prep(KP kp, unsigned char* shm) {
;     ...
;   for (size_t i0 = gtid; i0 < 2ull * 16 * 2048 * 16; i0 += 4 * gn) {
;     f32x4 a[4];
; #pragma unroll
;     for (int q = 0; q < 4; ++q) { const size_t i = i0 + q * gn; a[q] = i < 2ull * 16 * 2048 * 16 ? *(const f32x4*)(kp->cache_ik + i * 4) : (f32x4){0.f, 0.f, 0.f, 0.f}; }
.LBB0_2270:
	v_lshl_add_u64 v[2:3], s[16:17], 0, v[22:23]
	global_load_dwordx4 v[14:17], v[2:3], off nt
	v_lshl_add_u64 v[26:27], v[32:33], 0, s[8:9]
	v_cmp_gt_u64_e64 s[4:5], s[6:7], v[26:27]
	v_mov_b32_e32 v10, 0
	v_mov_b32_e32 v11, 0
	v_mov_b32_e32 v12, 0
	v_mov_b32_e32 v13, 0
	s_and_saveexec_b64 s[0:1], s[4:5]
	s_cbranch_execz .LBB0_2272
	v_lshl_add_u64 v[2:3], s[38:39], 0, v[22:23]
	global_load_dwordx4 v[10:13], v[2:3], off nt
.LBB0_2272:
	s_or_b64 exec, exec, s[0:1]
	v_lshl_add_u64 v[30:31], s[28:29], 0, v[32:33]
	v_cmp_gt_u64_e64 s[2:3], s[6:7], v[30:31]
	v_mov_b32_e32 v2, 0
	v_mov_b32_e32 v6, 0
	v_mov_b32_e32 v7, 0
	v_mov_b32_e32 v8, 0
	v_mov_b32_e32 v9, 0
	s_and_saveexec_b64 s[0:1], s[2:3]
	s_cbranch_execz .LBB0_2274
	v_lshl_add_u64 v[4:5], s[30:31], 0, v[22:23]
	global_load_dwordx4 v[6:9], v[4:5], off nt
.LBB0_2274:
	s_or_b64 exec, exec, s[0:1]
	v_lshl_add_u64 v[28:29], s[10:11], 0, v[32:33]
	v_cmp_gt_u64_e64 s[0:1], s[6:7], v[28:29]
	v_mov_b32_e32 v3, 0
	v_mov_b32_e32 v4, 0
	v_mov_b32_e32 v5, 0
	s_and_saveexec_b64 s[44:45], s[0:1]
	s_cbranch_execz .LBB0_2276
	v_lshl_add_u64 v[2:3], s[36:37], 0, v[22:23]
	global_load_dwordx4 v[2:5], v[2:3], off nt

; __device__ __forceinline__ void phase_prep(KP kp, unsigned char* shm) {
;     ...
;   for (size_t i = gtid; i < 2ull * 4 * 128 * 128; i += gn) {
;     const int s = (int)(i & 127), t = (int)((i >> 7) & 127);
;     const float v = s <= t ? kp->w_s[i] : 0.f;
;     ((bf16_t*)(ws + W_WSM))[i] = (bf16_t)(cvt_pk_bf16(v, 0.f) & 0xffffu);
; __global__ void __launch_bounds__(512, 2) mega(Params p_unused) {
;     ...
;   if (kp0->ws == nullptr) grid.sync();
.LBB0_2288:
	v_bfe_u32 v7, v36, 7, 7
	v_cmp_le_u32_e32 vcc, v1, v7
	v_mov_b32_e32 v7, 0
	s_and_saveexec_b64 s[12:13], vcc
	s_cbranch_execz .LBB0_2287
	s_load_dwordx2 s[14:15], s[20:21], 0x50
	s_waitcnt lgkmcnt(0)
	v_lshl_add_u64 v[8:9], s[14:15], 0, v[4:5]
	global_load_dword v7, v[8:9], off nt
	s_branch .LBB0_2287
.LBB0_2290:
	s_or_b64 exec, exec, s[0:1]
	v_readlane_b32 s0, v254, 2
	v_readlane_b32 s1, v254, 3
	s_load_dwordx2 s[0:1], s[0:1], 0xb0
	s_waitcnt lgkmcnt(0)
	s_cmp_lg_u64 s[0:1], 0
	s_cbranch_scc1 .LBB0_2302
	v_lshrrev_b32_e32 v1, 20, v0
	v_lshrrev_b32_e32 v0, 10, v0
	v_or_b32_e32 v0, v0, v1
	s_movk_i32 s0, 0x3ff
	v_and_or_b32 v0, v0, s0, v244
	v_cmp_eq_u32_e32 vcc, 0, v0
	s_barrier
	s_and_saveexec_b64 s[0:1], vcc
	s_cbranch_execz .LBB0_2301
	buffer_wbl2 sc1
	s_waitcnt vmcnt(0)
	s_load_dwordx2 s[2:3], s[18:19], 0x58
	v_mov_b32_e32 v2, 0
	s_mov_b64 s[4:5], exec
	v_mbcnt_lo_u32_b32 v1, s4, 0
	v_mbcnt_hi_u32_b32 v1, s5, v1
	s_waitcnt lgkmcnt(0)
	global_load_dword v0, v2, s[2:3] offset:40 nt
	v_cmp_eq_u32_e32 vcc, 0, v1
	s_and_saveexec_b64 s[6:7], vcc
	s_cbranch_execz .LBB0_2294
	s_bcnt1_i32_b64 s4, s[4:5]
	v_mov_b32_e32 v3, s4
	global_atomic_add v3, v2, v3, s[2:3] offset:32 sc0
